# simplification check: v30 without the next-unit attention prefetch and without the GEMM4a row-statistics prefetch
# baseline (speedup 1.0000x reference)
.LBB0_743:
	s_ashr_i32 s35, s34, 31
	s_lshl_b64 s[36:37], s[34:35], 17
	s_add_u32 s36, s13, s36
	s_addc_u32 s37, s22, s37
	s_and_b64 s[38:39], s[4:5], exec
	s_cselect_b32 s35, s37, s43
	s_cselect_b32 s82, s36, s42
	s_ashr_i32 s31, s30, 31
	s_lshl_b64 s[38:39], s[30:31], 17
	s_add_u32 s38, s23, s38
	s_addc_u32 s39, s58, s39
	s_and_b64 s[44:45], s[4:5], exec
	s_cselect_b32 s31, s39, s41
	s_cselect_b32 s83, s38, s40
	s_mov_b64 s[48:49], 0
	s_mov_b64 s[44:45], -1
	s_mov_b64 s[46:47], 0
	s_add_u32 s54, s42, s48
	s_addc_u32 s55, s43, s49
	s_add_u32 s52, s54, 0x100
	s_addc_u32 s53, s55, 0
	s_and_b64 s[50:51], s[46:47], exec
	s_cselect_b32 s51, s35, s53
	s_cselect_b32 s50, s82, s52
	s_add_u32 s48, s40, s48
	s_addc_u32 s49, s41, s49
	s_add_u32 s48, s48, 0x100
	s_addc_u32 s49, s49, 0
	s_and_b64 s[46:47], s[46:47], exec
	s_cselect_b32 s53, s31, s49
	s_cselect_b32 s52, s83, s48
	s_add_u32 s56, s54, 0x10080
	ds_read_b128 v[150:153], v144
	ds_read_b128 v[154:157], v144 offset:1024
	ds_read_b128 v[158:161], v144 offset:2048
	ds_read_b128 v[162:165], v144 offset:3072
	ds_read_b128 v[166:169], v145
	ds_read_b128 v[170:173], v145 offset:1024
	ds_read_b128 v[174:177], v145 offset:2048
	ds_read_b128 v[178:181], v145 offset:3072
	s_addc_u32 s57, s55, 0
	s_add_i32 s93, s74, s60
	s_add_i32 m0, s61, 0xc000
	s_add_i32 s94, s61, 0xe000
	s_add_i32 s90, s93, 0x2000
	s_add_u32 s54, s52, 0x10000
	s_addc_u32 s55, s53, 0
	s_add_i32 s92, s75, s60
	s_add_i32 s91, s92, 0x2000
	s_add_i32 s89, 0, 0x18000
	s_add_i32 s88, 0, 0x1c000
	s_add_u32 s48, s50, 0x10000
	s_addc_u32 s49, s51, 0
	s_add_i32 s87, s89, s60
	s_add_i32 s85, s87, 0x2000
	s_add_u32 s46, s52, 0x10080
	s_addc_u32 s47, s53, 0
	s_add_i32 s86, s88, s60
	s_add_i32 s84, s86, 0x2000
	v_lshl_add_u64 v[138:139], s[56:57], 0, v[130:131]
	ds_read_b128 v[182:185], v146
	ds_read_b128 v[186:189], v146 offset:1024
	ds_read_b128 v[190:193], v146 offset:2048
	ds_read_b128 v[194:197], v146 offset:3072
	ds_read_b128 v[198:201], v146 offset:4096
	ds_read_b128 v[202:205], v146 offset:5120
	ds_read_b128 v[206:209], v146 offset:6144
	ds_read_b128 v[210:213], v146 offset:7168
	global_load_lds_dwordx4 v[138:139], off
	v_lshl_add_u64 v[138:139], s[56:57], 0, v[128:129]
	s_mov_b32 m0, s94
	s_nop 0
	global_load_lds_dwordx4 v[138:139], off
	s_waitcnt vmcnt(8)
	s_waitcnt lgkmcnt(0)
	s_setprio 1
	s_barrier
	v_mfma_f32_16x16x32_bf16 v[124:127], v[150:153], v[182:185], 0
	v_mfma_f32_16x16x32_bf16 v[120:123], v[158:161], v[182:185], 0
	v_mfma_f32_16x16x32_bf16 v[108:111], v[150:153], v[190:193], 0
	v_mfma_f32_16x16x32_bf16 v[104:107], v[158:161], v[190:193], 0
	v_mfma_f32_16x16x32_bf16 v[92:95], v[150:153], v[198:201], 0
	v_mfma_f32_16x16x32_bf16 v[88:91], v[158:161], v[198:201], 0
	v_mfma_f32_16x16x32_bf16 v[76:79], v[150:153], v[206:209], 0
	v_mfma_f32_16x16x32_bf16 v[72:75], v[158:161], v[206:209], 0
	v_mfma_f32_16x16x32_bf16 v[124:127], v[154:157], v[186:189], v[124:127]
	v_mfma_f32_16x16x32_bf16 v[120:123], v[162:165], v[186:189], v[120:123]
	v_mfma_f32_16x16x32_bf16 v[108:111], v[154:157], v[194:197], v[108:111]
	v_mfma_f32_16x16x32_bf16 v[104:107], v[162:165], v[194:197], v[104:107]
	v_mfma_f32_16x16x32_bf16 v[92:95], v[154:157], v[202:205], v[92:95]
	v_mfma_f32_16x16x32_bf16 v[88:91], v[162:165], v[202:205], v[88:91]
	v_mfma_f32_16x16x32_bf16 v[76:79], v[154:157], v[210:213], v[76:79]
	v_mfma_f32_16x16x32_bf16 v[72:75], v[162:165], v[210:213], v[72:75]
	v_mfma_f32_16x16x32_bf16 v[116:119], v[166:169], v[182:185], 0
	v_mfma_f32_16x16x32_bf16 v[112:115], v[174:177], v[182:185], 0
	v_mfma_f32_16x16x32_bf16 v[100:103], v[166:169], v[190:193], 0
	v_mfma_f32_16x16x32_bf16 v[96:99], v[174:177], v[190:193], 0
	v_mfma_f32_16x16x32_bf16 v[84:87], v[166:169], v[198:201], 0
	v_mfma_f32_16x16x32_bf16 v[80:83], v[174:177], v[198:201], 0
	v_mfma_f32_16x16x32_bf16 v[68:71], v[166:169], v[206:209], 0
	v_mfma_f32_16x16x32_bf16 v[64:67], v[174:177], v[206:209], 0
	v_mfma_f32_16x16x32_bf16 v[116:119], v[170:173], v[186:189], v[116:119]
	v_mfma_f32_16x16x32_bf16 v[112:115], v[178:181], v[186:189], v[112:115]
	v_mfma_f32_16x16x32_bf16 v[100:103], v[170:173], v[194:197], v[100:103]
	v_mfma_f32_16x16x32_bf16 v[96:99], v[178:181], v[194:197], v[96:99]
	v_mfma_f32_16x16x32_bf16 v[84:87], v[170:173], v[202:205], v[84:87]
	v_mfma_f32_16x16x32_bf16 v[80:83], v[178:181], v[202:205], v[80:83]
	v_mfma_f32_16x16x32_bf16 v[68:71], v[170:173], v[210:213], v[68:71]
	v_mfma_f32_16x16x32_bf16 v[64:67], v[178:181], v[210:213], v[64:67]
	s_barrier
	s_setprio 0
	s_mov_b32 m0, s93
	v_lshl_add_u64 v[138:139], s[52:53], 0, v[130:131]
	ds_read_b128 v[182:185], v146 offset:16384
	ds_read_b128 v[186:189], v146 offset:17408
	ds_read_b128 v[190:193], v146 offset:18432
	ds_read_b128 v[194:197], v146 offset:19456
	ds_read_b128 v[198:201], v146 offset:20480
	ds_read_b128 v[202:205], v146 offset:21504
	ds_read_b128 v[206:209], v146 offset:22528
	ds_read_b128 v[210:213], v146 offset:23552
	global_load_lds_dwordx4 v[138:139], off
	v_lshl_add_u64 v[214:215], s[52:53], 0, v[128:129]
	s_mov_b32 m0, s90
	v_lshl_add_u64 v[216:217], s[54:55], 0, v[130:131]
	global_load_lds_dwordx4 v[214:215], off
	s_mov_b32 m0, s92
	v_lshl_add_u64 v[218:219], s[50:51], 0, v[128:129]
	global_load_lds_dwordx4 v[216:217], off
	v_lshl_add_u64 v[216:217], s[54:55], 0, v[128:129]
	s_mov_b32 m0, s91
	s_nop 0
	global_load_lds_dwordx4 v[216:217], off
	v_lshl_add_u64 v[216:217], s[50:51], 0, v[130:131]
	s_mov_b32 m0, s61
	s_nop 0
	global_load_lds_dwordx4 v[216:217], off
	s_mov_b32 m0, s62
	s_nop 0
	global_load_lds_dwordx4 v[218:219], off
	s_waitcnt vmcnt(8)
	s_waitcnt lgkmcnt(0)
	s_setprio 1
	s_barrier
	v_mfma_f32_16x16x32_bf16 v[60:63], v[150:153], v[182:185], 0
	v_mfma_f32_16x16x32_bf16 v[56:59], v[158:161], v[182:185], 0
	v_mfma_f32_16x16x32_bf16 v[44:47], v[150:153], v[190:193], 0
	v_mfma_f32_16x16x32_bf16 v[40:43], v[158:161], v[190:193], 0
	v_mfma_f32_16x16x32_bf16 v[28:31], v[150:153], v[198:201], 0
	v_mfma_f32_16x16x32_bf16 v[24:27], v[158:161], v[198:201], 0
	v_mfma_f32_16x16x32_bf16 v[12:15], v[150:153], v[206:209], 0
	v_mfma_f32_16x16x32_bf16 v[8:11], v[158:161], v[206:209], 0
	v_mfma_f32_16x16x32_bf16 v[60:63], v[154:157], v[186:189], v[60:63]
	v_mfma_f32_16x16x32_bf16 v[56:59], v[162:165], v[186:189], v[56:59]
	v_mfma_f32_16x16x32_bf16 v[44:47], v[154:157], v[194:197], v[44:47]
	v_mfma_f32_16x16x32_bf16 v[40:43], v[162:165], v[194:197], v[40:43]
	v_mfma_f32_16x16x32_bf16 v[28:31], v[154:157], v[202:205], v[28:31]
	v_mfma_f32_16x16x32_bf16 v[24:27], v[162:165], v[202:205], v[24:27]
	v_mfma_f32_16x16x32_bf16 v[12:15], v[154:157], v[210:213], v[12:15]
	v_mfma_f32_16x16x32_bf16 v[8:11], v[162:165], v[210:213], v[8:11]
	v_mfma_f32_16x16x32_bf16 v[52:55], v[166:169], v[182:185], 0
	v_mfma_f32_16x16x32_bf16 v[48:51], v[174:177], v[182:185], 0
	v_mfma_f32_16x16x32_bf16 v[36:39], v[166:169], v[190:193], 0
	v_mfma_f32_16x16x32_bf16 v[32:35], v[174:177], v[190:193], 0
	v_mfma_f32_16x16x32_bf16 v[20:23], v[166:169], v[198:201], 0
	v_mfma_f32_16x16x32_bf16 v[16:19], v[174:177], v[198:201], 0
	v_mfma_f32_16x16x32_bf16 v[4:7], v[166:169], v[206:209], 0
	v_mfma_f32_16x16x32_bf16 v[0:3], v[174:177], v[206:209], 0
	v_mfma_f32_16x16x32_bf16 v[52:55], v[170:173], v[186:189], v[52:55]
	v_mfma_f32_16x16x32_bf16 v[48:51], v[178:181], v[186:189], v[48:51]
	v_mfma_f32_16x16x32_bf16 v[36:39], v[170:173], v[194:197], v[36:39]
	v_mfma_f32_16x16x32_bf16 v[32:35], v[178:181], v[194:197], v[32:35]
	v_mfma_f32_16x16x32_bf16 v[20:23], v[170:173], v[202:205], v[20:23]
	v_mfma_f32_16x16x32_bf16 v[16:19], v[178:181], v[202:205], v[16:19]
	v_mfma_f32_16x16x32_bf16 v[4:7], v[170:173], v[210:213], v[4:7]
	v_mfma_f32_16x16x32_bf16 v[0:3], v[178:181], v[210:213], v[0:3]
	s_barrier
	s_setprio 0
	v_add_u32_e32 v132, s89, v143
	ds_read_b128 v[150:153], v132
	ds_read_b128 v[154:157], v132 offset:1024
	ds_read_b128 v[158:161], v132 offset:2048
	ds_read_b128 v[162:165], v132 offset:3072
	v_add_u32_e32 v132, s88, v143
	ds_read_b128 v[166:169], v132
	ds_read_b128 v[170:173], v132 offset:1024
	ds_read_b128 v[174:177], v132 offset:2048
	ds_read_b128 v[178:181], v132 offset:3072
	s_mov_b32 m0, s63
	v_lshl_add_u64 v[220:221], s[48:49], 0, v[130:131]
	ds_read_b128 v[182:185], v146 offset:32768
	ds_read_b128 v[186:189], v146 offset:33792
	ds_read_b128 v[190:193], v146 offset:34816
	ds_read_b128 v[194:197], v146 offset:35840
	ds_read_b128 v[198:201], v146 offset:36864
	ds_read_b128 v[202:205], v146 offset:37888
	ds_read_b128 v[206:209], v146 offset:38912
	ds_read_b128 v[210:213], v146 offset:39936
	global_load_lds_dwordx4 v[220:221], off
	v_lshl_add_u64 v[220:221], s[48:49], 0, v[128:129]
	s_mov_b32 m0, s64
	s_nop 0
	global_load_lds_dwordx4 v[220:221], off
	s_waitcnt vmcnt(8)
	s_waitcnt lgkmcnt(0)
	s_setprio 1
	s_barrier
	v_mfma_f32_16x16x32_bf16 v[124:127], v[150:153], v[182:185], v[124:127]
	v_mfma_f32_16x16x32_bf16 v[120:123], v[158:161], v[182:185], v[120:123]
	v_mfma_f32_16x16x32_bf16 v[108:111], v[150:153], v[190:193], v[108:111]
	v_mfma_f32_16x16x32_bf16 v[104:107], v[158:161], v[190:193], v[104:107]
	v_mfma_f32_16x16x32_bf16 v[92:95], v[150:153], v[198:201], v[92:95]
	v_mfma_f32_16x16x32_bf16 v[88:91], v[158:161], v[198:201], v[88:91]
	v_mfma_f32_16x16x32_bf16 v[76:79], v[150:153], v[206:209], v[76:79]
	v_mfma_f32_16x16x32_bf16 v[72:75], v[158:161], v[206:209], v[72:75]
	v_mfma_f32_16x16x32_bf16 v[124:127], v[154:157], v[186:189], v[124:127]
	v_mfma_f32_16x16x32_bf16 v[120:123], v[162:165], v[186:189], v[120:123]
	v_mfma_f32_16x16x32_bf16 v[108:111], v[154:157], v[194:197], v[108:111]
	v_mfma_f32_16x16x32_bf16 v[104:107], v[162:165], v[194:197], v[104:107]
	v_mfma_f32_16x16x32_bf16 v[92:95], v[154:157], v[202:205], v[92:95]
	v_mfma_f32_16x16x32_bf16 v[88:91], v[162:165], v[202:205], v[88:91]
	v_mfma_f32_16x16x32_bf16 v[76:79], v[154:157], v[210:213], v[76:79]
	v_mfma_f32_16x16x32_bf16 v[72:75], v[162:165], v[210:213], v[72:75]
	v_mfma_f32_16x16x32_bf16 v[116:119], v[166:169], v[182:185], v[116:119]
	v_mfma_f32_16x16x32_bf16 v[112:115], v[174:177], v[182:185], v[112:115]
	v_mfma_f32_16x16x32_bf16 v[100:103], v[166:169], v[190:193], v[100:103]
	v_mfma_f32_16x16x32_bf16 v[96:99], v[174:177], v[190:193], v[96:99]
	v_mfma_f32_16x16x32_bf16 v[84:87], v[166:169], v[198:201], v[84:87]
	v_mfma_f32_16x16x32_bf16 v[80:83], v[174:177], v[198:201], v[80:83]
	v_mfma_f32_16x16x32_bf16 v[68:71], v[166:169], v[206:209], v[68:71]
	v_mfma_f32_16x16x32_bf16 v[64:67], v[174:177], v[206:209], v[64:67]
	v_mfma_f32_16x16x32_bf16 v[116:119], v[170:173], v[186:189], v[116:119]
	v_mfma_f32_16x16x32_bf16 v[112:115], v[178:181], v[186:189], v[112:115]
	v_mfma_f32_16x16x32_bf16 v[100:103], v[170:173], v[194:197], v[100:103]
	v_mfma_f32_16x16x32_bf16 v[96:99], v[178:181], v[194:197], v[96:99]
	v_mfma_f32_16x16x32_bf16 v[84:87], v[170:173], v[202:205], v[84:87]
	v_mfma_f32_16x16x32_bf16 v[80:83], v[178:181], v[202:205], v[80:83]
	v_mfma_f32_16x16x32_bf16 v[68:71], v[170:173], v[210:213], v[68:71]
	v_mfma_f32_16x16x32_bf16 v[64:67], v[178:181], v[210:213], v[64:67]
	s_barrier
	s_setprio 0
	s_mov_b32 m0, s87
	v_lshl_add_u64 v[138:139], v[138:139], 0, s[16:17]
	ds_read_b128 v[182:185], v146 offset:49152
	ds_read_b128 v[186:189], v146 offset:50176
	ds_read_b128 v[190:193], v146 offset:51200
	ds_read_b128 v[194:197], v146 offset:52224
	ds_read_b128 v[198:201], v146 offset:53248
	ds_read_b128 v[202:205], v146 offset:54272
	ds_read_b128 v[206:209], v146 offset:55296
	ds_read_b128 v[210:213], v146 offset:56320
	global_load_lds_dwordx4 v[138:139], off
	v_lshl_add_u64 v[138:139], v[214:215], 0, s[16:17]
	s_mov_b32 m0, s85
	s_nop 0
	global_load_lds_dwordx4 v[138:139], off
	v_lshl_add_u64 v[138:139], s[46:47], 0, v[130:131]
	s_mov_b32 m0, s86
	s_nop 0
	global_load_lds_dwordx4 v[138:139], off
	v_lshl_add_u64 v[138:139], s[46:47], 0, v[128:129]
	s_mov_b32 m0, s84
	s_nop 0
	global_load_lds_dwordx4 v[138:139], off
	v_lshl_add_u64 v[138:139], v[216:217], 0, s[16:17]
	s_mov_b32 m0, s70
	s_nop 0
	global_load_lds_dwordx4 v[138:139], off
	v_lshl_add_u64 v[138:139], v[218:219], 0, s[16:17]
	s_mov_b32 m0, s71
	s_nop 0
	global_load_lds_dwordx4 v[138:139], off
	s_waitcnt vmcnt(8)
	s_waitcnt lgkmcnt(0)
	s_setprio 1
	s_barrier
	v_mfma_f32_16x16x32_bf16 v[60:63], v[150:153], v[182:185], v[60:63]
	v_mfma_f32_16x16x32_bf16 v[56:59], v[158:161], v[182:185], v[56:59]
	v_mfma_f32_16x16x32_bf16 v[44:47], v[150:153], v[190:193], v[44:47]
	v_mfma_f32_16x16x32_bf16 v[40:43], v[158:161], v[190:193], v[40:43]
	v_mfma_f32_16x16x32_bf16 v[28:31], v[150:153], v[198:201], v[28:31]
	v_mfma_f32_16x16x32_bf16 v[24:27], v[158:161], v[198:201], v[24:27]
	v_mfma_f32_16x16x32_bf16 v[12:15], v[150:153], v[206:209], v[12:15]
	v_mfma_f32_16x16x32_bf16 v[8:11], v[158:161], v[206:209], v[8:11]
	v_mfma_f32_16x16x32_bf16 v[60:63], v[154:157], v[186:189], v[60:63]
	v_mfma_f32_16x16x32_bf16 v[56:59], v[162:165], v[186:189], v[56:59]
	v_mfma_f32_16x16x32_bf16 v[44:47], v[154:157], v[194:197], v[44:47]
	v_mfma_f32_16x16x32_bf16 v[40:43], v[162:165], v[194:197], v[40:43]
	v_mfma_f32_16x16x32_bf16 v[28:31], v[154:157], v[202:205], v[28:31]
	v_mfma_f32_16x16x32_bf16 v[24:27], v[162:165], v[202:205], v[24:27]
	v_mfma_f32_16x16x32_bf16 v[12:15], v[154:157], v[210:213], v[12:15]
	v_mfma_f32_16x16x32_bf16 v[8:11], v[162:165], v[210:213], v[8:11]
	v_mfma_f32_16x16x32_bf16 v[52:55], v[166:169], v[182:185], v[52:55]
	v_mfma_f32_16x16x32_bf16 v[48:51], v[174:177], v[182:185], v[48:51]
	v_mfma_f32_16x16x32_bf16 v[36:39], v[166:169], v[190:193], v[36:39]
	v_mfma_f32_16x16x32_bf16 v[32:35], v[174:177], v[190:193], v[32:35]
	v_mfma_f32_16x16x32_bf16 v[20:23], v[166:169], v[198:201], v[20:23]
	v_mfma_f32_16x16x32_bf16 v[16:19], v[174:177], v[198:201], v[16:19]
	v_mfma_f32_16x16x32_bf16 v[4:7], v[166:169], v[206:209], v[4:7]
	v_mfma_f32_16x16x32_bf16 v[0:3], v[174:177], v[206:209], v[0:3]
	v_mfma_f32_16x16x32_bf16 v[52:55], v[170:173], v[186:189], v[52:55]
	v_mfma_f32_16x16x32_bf16 v[48:51], v[178:181], v[186:189], v[48:51]
	v_mfma_f32_16x16x32_bf16 v[36:39], v[170:173], v[194:197], v[36:39]
	v_mfma_f32_16x16x32_bf16 v[32:35], v[178:181], v[194:197], v[32:35]
	v_mfma_f32_16x16x32_bf16 v[20:23], v[170:173], v[202:205], v[20:23]
	v_mfma_f32_16x16x32_bf16 v[16:19], v[178:181], v[202:205], v[16:19]
	v_mfma_f32_16x16x32_bf16 v[4:7], v[170:173], v[210:213], v[4:7]
	v_mfma_f32_16x16x32_bf16 v[0:3], v[178:181], v[210:213], v[0:3]
	s_barrier
	s_setprio 0
	s_andn2_b64 vcc, exec, s[44:45]
	s_mov_b64 s[46:47], -1
	s_mov_b64 s[44:45], 0
	s_mov_b64 s[48:49], 0x100
	s_cbranch_vccnz .Lkx_744
.LBB0_744:
	s_add_u32 s54, s42, s48
	s_addc_u32 s55, s43, s49
	s_add_u32 s52, s54, 0x100
	s_addc_u32 s53, s55, 0
	s_and_b64 s[50:51], s[46:47], exec
	s_cselect_b32 s51, s35, s53
	s_cselect_b32 s50, s82, s52
	s_add_u32 s48, s40, s48
	s_addc_u32 s49, s41, s49
	s_add_u32 s48, s48, 0x100
	s_addc_u32 s49, s49, 0
	s_and_b64 s[46:47], s[46:47], exec
	s_cselect_b32 s53, s31, s49
	s_cselect_b32 s52, s83, s48
	s_add_u32 s56, s54, 0x10080
	ds_read_b128 v[150:153], v144
	ds_read_b128 v[154:157], v144 offset:1024
	ds_read_b128 v[158:161], v144 offset:2048
	ds_read_b128 v[162:165], v144 offset:3072
	ds_read_b128 v[166:169], v145
	ds_read_b128 v[170:173], v145 offset:1024
	ds_read_b128 v[174:177], v145 offset:2048
	ds_read_b128 v[178:181], v145 offset:3072
	s_addc_u32 s57, s55, 0
	s_add_i32 s93, s74, s60
	s_add_i32 m0, s61, 0xc000
	s_add_i32 s94, s61, 0xe000
	s_add_i32 s90, s93, 0x2000
	s_add_u32 s54, s52, 0x10000
	s_addc_u32 s55, s53, 0
	s_add_i32 s92, s75, s60
	s_add_i32 s91, s92, 0x2000
	s_add_i32 s89, 0, 0x18000
	s_add_i32 s88, 0, 0x1c000
	s_add_u32 s48, s50, 0x10000
	s_addc_u32 s49, s51, 0
	s_add_i32 s87, s89, s60
	s_add_i32 s85, s87, 0x2000
	s_add_u32 s46, s52, 0x10080
	s_addc_u32 s47, s53, 0
	s_add_i32 s86, s88, s60
	s_add_i32 s84, s86, 0x2000
	v_lshl_add_u64 v[138:139], s[56:57], 0, v[130:131]
	ds_read_b128 v[182:185], v146
	ds_read_b128 v[186:189], v146 offset:1024
	ds_read_b128 v[190:193], v146 offset:2048
	ds_read_b128 v[194:197], v146 offset:3072
	ds_read_b128 v[198:201], v146 offset:4096
	ds_read_b128 v[202:205], v146 offset:5120
	ds_read_b128 v[206:209], v146 offset:6144
	ds_read_b128 v[210:213], v146 offset:7168
	global_load_lds_dwordx4 v[138:139], off
	v_lshl_add_u64 v[138:139], s[56:57], 0, v[128:129]
	s_mov_b32 m0, s94
	s_nop 0
	global_load_lds_dwordx4 v[138:139], off
	s_waitcnt vmcnt(8)
	s_waitcnt lgkmcnt(0)
	s_setprio 1
	s_barrier
	v_mfma_f32_16x16x32_bf16 v[124:127], v[150:153], v[182:185], v[124:127]
	v_mfma_f32_16x16x32_bf16 v[120:123], v[158:161], v[182:185], v[120:123]
	v_mfma_f32_16x16x32_bf16 v[108:111], v[150:153], v[190:193], v[108:111]
	v_mfma_f32_16x16x32_bf16 v[104:107], v[158:161], v[190:193], v[104:107]
	v_mfma_f32_16x16x32_bf16 v[92:95], v[150:153], v[198:201], v[92:95]
	v_mfma_f32_16x16x32_bf16 v[88:91], v[158:161], v[198:201], v[88:91]
	v_mfma_f32_16x16x32_bf16 v[76:79], v[150:153], v[206:209], v[76:79]
	v_mfma_f32_16x16x32_bf16 v[72:75], v[158:161], v[206:209], v[72:75]
	v_mfma_f32_16x16x32_bf16 v[124:127], v[154:157], v[186:189], v[124:127]
	v_mfma_f32_16x16x32_bf16 v[120:123], v[162:165], v[186:189], v[120:123]
	v_mfma_f32_16x16x32_bf16 v[108:111], v[154:157], v[194:197], v[108:111]
	v_mfma_f32_16x16x32_bf16 v[104:107], v[162:165], v[194:197], v[104:107]
	v_mfma_f32_16x16x32_bf16 v[92:95], v[154:157], v[202:205], v[92:95]
	v_mfma_f32_16x16x32_bf16 v[88:91], v[162:165], v[202:205], v[88:91]
	v_mfma_f32_16x16x32_bf16 v[76:79], v[154:157], v[210:213], v[76:79]
	v_mfma_f32_16x16x32_bf16 v[72:75], v[162:165], v[210:213], v[72:75]
	v_mfma_f32_16x16x32_bf16 v[116:119], v[166:169], v[182:185], v[116:119]
	v_mfma_f32_16x16x32_bf16 v[112:115], v[174:177], v[182:185], v[112:115]
	v_mfma_f32_16x16x32_bf16 v[100:103], v[166:169], v[190:193], v[100:103]
	v_mfma_f32_16x16x32_bf16 v[96:99], v[174:177], v[190:193], v[96:99]
	v_mfma_f32_16x16x32_bf16 v[84:87], v[166:169], v[198:201], v[84:87]
	v_mfma_f32_16x16x32_bf16 v[80:83], v[174:177], v[198:201], v[80:83]
	v_mfma_f32_16x16x32_bf16 v[68:71], v[166:169], v[206:209], v[68:71]
	v_mfma_f32_16x16x32_bf16 v[64:67], v[174:177], v[206:209], v[64:67]
	v_mfma_f32_16x16x32_bf16 v[116:119], v[170:173], v[186:189], v[116:119]
	v_mfma_f32_16x16x32_bf16 v[112:115], v[178:181], v[186:189], v[112:115]
	v_mfma_f32_16x16x32_bf16 v[100:103], v[170:173], v[194:197], v[100:103]
	v_mfma_f32_16x16x32_bf16 v[96:99], v[178:181], v[194:197], v[96:99]
	v_mfma_f32_16x16x32_bf16 v[84:87], v[170:173], v[202:205], v[84:87]
	v_mfma_f32_16x16x32_bf16 v[80:83], v[178:181], v[202:205], v[80:83]
	v_mfma_f32_16x16x32_bf16 v[68:71], v[170:173], v[210:213], v[68:71]
	v_mfma_f32_16x16x32_bf16 v[64:67], v[178:181], v[210:213], v[64:67]
	s_barrier
	s_setprio 0
	s_mov_b32 m0, s93
	v_lshl_add_u64 v[138:139], s[52:53], 0, v[130:131]
	ds_read_b128 v[182:185], v146 offset:16384
	ds_read_b128 v[186:189], v146 offset:17408
	ds_read_b128 v[190:193], v146 offset:18432
	ds_read_b128 v[194:197], v146 offset:19456
	ds_read_b128 v[198:201], v146 offset:20480
	ds_read_b128 v[202:205], v146 offset:21504
	ds_read_b128 v[206:209], v146 offset:22528
	ds_read_b128 v[210:213], v146 offset:23552
	global_load_lds_dwordx4 v[138:139], off
	v_lshl_add_u64 v[214:215], s[52:53], 0, v[128:129]
	s_mov_b32 m0, s90
	v_lshl_add_u64 v[216:217], s[54:55], 0, v[130:131]
	global_load_lds_dwordx4 v[214:215], off
	s_mov_b32 m0, s92
	v_lshl_add_u64 v[218:219], s[50:51], 0, v[128:129]
	global_load_lds_dwordx4 v[216:217], off
	v_lshl_add_u64 v[216:217], s[54:55], 0, v[128:129]
	s_mov_b32 m0, s91
	s_nop 0
	global_load_lds_dwordx4 v[216:217], off
	v_lshl_add_u64 v[216:217], s[50:51], 0, v[130:131]
	s_mov_b32 m0, s61
	s_nop 0
	global_load_lds_dwordx4 v[216:217], off
	s_mov_b32 m0, s62
	s_nop 0
	global_load_lds_dwordx4 v[218:219], off
	s_waitcnt vmcnt(8)
	s_waitcnt lgkmcnt(0)
	s_setprio 1
	s_barrier
	v_mfma_f32_16x16x32_bf16 v[60:63], v[150:153], v[182:185], v[60:63]
	v_mfma_f32_16x16x32_bf16 v[56:59], v[158:161], v[182:185], v[56:59]
	v_mfma_f32_16x16x32_bf16 v[44:47], v[150:153], v[190:193], v[44:47]
	v_mfma_f32_16x16x32_bf16 v[40:43], v[158:161], v[190:193], v[40:43]
	v_mfma_f32_16x16x32_bf16 v[28:31], v[150:153], v[198:201], v[28:31]
	v_mfma_f32_16x16x32_bf16 v[24:27], v[158:161], v[198:201], v[24:27]
	v_mfma_f32_16x16x32_bf16 v[12:15], v[150:153], v[206:209], v[12:15]
	v_mfma_f32_16x16x32_bf16 v[8:11], v[158:161], v[206:209], v[8:11]
	v_mfma_f32_16x16x32_bf16 v[60:63], v[154:157], v[186:189], v[60:63]
	v_mfma_f32_16x16x32_bf16 v[56:59], v[162:165], v[186:189], v[56:59]
	v_mfma_f32_16x16x32_bf16 v[44:47], v[154:157], v[194:197], v[44:47]
	v_mfma_f32_16x16x32_bf16 v[40:43], v[162:165], v[194:197], v[40:43]
	v_mfma_f32_16x16x32_bf16 v[28:31], v[154:157], v[202:205], v[28:31]
	v_mfma_f32_16x16x32_bf16 v[24:27], v[162:165], v[202:205], v[24:27]
	v_mfma_f32_16x16x32_bf16 v[12:15], v[154:157], v[210:213], v[12:15]
	v_mfma_f32_16x16x32_bf16 v[8:11], v[162:165], v[210:213], v[8:11]
	v_mfma_f32_16x16x32_bf16 v[52:55], v[166:169], v[182:185], v[52:55]
	v_mfma_f32_16x16x32_bf16 v[48:51], v[174:177], v[182:185], v[48:51]
	v_mfma_f32_16x16x32_bf16 v[36:39], v[166:169], v[190:193], v[36:39]
	v_mfma_f32_16x16x32_bf16 v[32:35], v[174:177], v[190:193], v[32:35]
	v_mfma_f32_16x16x32_bf16 v[20:23], v[166:169], v[198:201], v[20:23]
	v_mfma_f32_16x16x32_bf16 v[16:19], v[174:177], v[198:201], v[16:19]
	v_mfma_f32_16x16x32_bf16 v[4:7], v[166:169], v[206:209], v[4:7]
	v_mfma_f32_16x16x32_bf16 v[0:3], v[174:177], v[206:209], v[0:3]
	v_mfma_f32_16x16x32_bf16 v[52:55], v[170:173], v[186:189], v[52:55]
	v_mfma_f32_16x16x32_bf16 v[48:51], v[178:181], v[186:189], v[48:51]
	v_mfma_f32_16x16x32_bf16 v[36:39], v[170:173], v[194:197], v[36:39]
	v_mfma_f32_16x16x32_bf16 v[32:35], v[178:181], v[194:197], v[32:35]
	v_mfma_f32_16x16x32_bf16 v[20:23], v[170:173], v[202:205], v[20:23]
	v_mfma_f32_16x16x32_bf16 v[16:19], v[178:181], v[202:205], v[16:19]
	v_mfma_f32_16x16x32_bf16 v[4:7], v[170:173], v[210:213], v[4:7]
	v_mfma_f32_16x16x32_bf16 v[0:3], v[178:181], v[210:213], v[0:3]
	s_barrier
	s_setprio 0
	v_add_u32_e32 v132, s89, v143
	ds_read_b128 v[150:153], v132
	ds_read_b128 v[154:157], v132 offset:1024
	ds_read_b128 v[158:161], v132 offset:2048
	ds_read_b128 v[162:165], v132 offset:3072
	v_add_u32_e32 v132, s88, v143
	ds_read_b128 v[166:169], v132
	ds_read_b128 v[170:173], v132 offset:1024
	ds_read_b128 v[174:177], v132 offset:2048
	ds_read_b128 v[178:181], v132 offset:3072
	s_mov_b32 m0, s63
	v_lshl_add_u64 v[220:221], s[48:49], 0, v[130:131]
	ds_read_b128 v[182:185], v146 offset:32768
	ds_read_b128 v[186:189], v146 offset:33792
	ds_read_b128 v[190:193], v146 offset:34816
	ds_read_b128 v[194:197], v146 offset:35840
	ds_read_b128 v[198:201], v146 offset:36864
	ds_read_b128 v[202:205], v146 offset:37888
	ds_read_b128 v[206:209], v146 offset:38912
	ds_read_b128 v[210:213], v146 offset:39936
	global_load_lds_dwordx4 v[220:221], off
	v_lshl_add_u64 v[220:221], s[48:49], 0, v[128:129]
	s_mov_b32 m0, s64
	s_nop 0
	global_load_lds_dwordx4 v[220:221], off
	s_waitcnt vmcnt(8)
	s_waitcnt lgkmcnt(0)
	s_setprio 1
	s_barrier
	v_mfma_f32_16x16x32_bf16 v[124:127], v[150:153], v[182:185], v[124:127]
	v_mfma_f32_16x16x32_bf16 v[120:123], v[158:161], v[182:185], v[120:123]
	v_mfma_f32_16x16x32_bf16 v[108:111], v[150:153], v[190:193], v[108:111]
	v_mfma_f32_16x16x32_bf16 v[104:107], v[158:161], v[190:193], v[104:107]
	v_mfma_f32_16x16x32_bf16 v[92:95], v[150:153], v[198:201], v[92:95]
	v_mfma_f32_16x16x32_bf16 v[88:91], v[158:161], v[198:201], v[88:91]
	v_mfma_f32_16x16x32_bf16 v[76:79], v[150:153], v[206:209], v[76:79]
	v_mfma_f32_16x16x32_bf16 v[72:75], v[158:161], v[206:209], v[72:75]
	v_mfma_f32_16x16x32_bf16 v[124:127], v[154:157], v[186:189], v[124:127]
	v_mfma_f32_16x16x32_bf16 v[120:123], v[162:165], v[186:189], v[120:123]
	v_mfma_f32_16x16x32_bf16 v[108:111], v[154:157], v[194:197], v[108:111]
	v_mfma_f32_16x16x32_bf16 v[104:107], v[162:165], v[194:197], v[104:107]
	v_mfma_f32_16x16x32_bf16 v[92:95], v[154:157], v[202:205], v[92:95]
	v_mfma_f32_16x16x32_bf16 v[88:91], v[162:165], v[202:205], v[88:91]
	v_mfma_f32_16x16x32_bf16 v[76:79], v[154:157], v[210:213], v[76:79]
	v_mfma_f32_16x16x32_bf16 v[72:75], v[162:165], v[210:213], v[72:75]
	v_mfma_f32_16x16x32_bf16 v[116:119], v[166:169], v[182:185], v[116:119]
	v_mfma_f32_16x16x32_bf16 v[112:115], v[174:177], v[182:185], v[112:115]
	v_mfma_f32_16x16x32_bf16 v[100:103], v[166:169], v[190:193], v[100:103]
	v_mfma_f32_16x16x32_bf16 v[96:99], v[174:177], v[190:193], v[96:99]
	v_mfma_f32_16x16x32_bf16 v[84:87], v[166:169], v[198:201], v[84:87]
	v_mfma_f32_16x16x32_bf16 v[80:83], v[174:177], v[198:201], v[80:83]
	v_mfma_f32_16x16x32_bf16 v[68:71], v[166:169], v[206:209], v[68:71]
	v_mfma_f32_16x16x32_bf16 v[64:67], v[174:177], v[206:209], v[64:67]
	v_mfma_f32_16x16x32_bf16 v[116:119], v[170:173], v[186:189], v[116:119]
	v_mfma_f32_16x16x32_bf16 v[112:115], v[178:181], v[186:189], v[112:115]
	v_mfma_f32_16x16x32_bf16 v[100:103], v[170:173], v[194:197], v[100:103]
	v_mfma_f32_16x16x32_bf16 v[96:99], v[178:181], v[194:197], v[96:99]
	v_mfma_f32_16x16x32_bf16 v[84:87], v[170:173], v[202:205], v[84:87]
	v_mfma_f32_16x16x32_bf16 v[80:83], v[178:181], v[202:205], v[80:83]
	v_mfma_f32_16x16x32_bf16 v[68:71], v[170:173], v[210:213], v[68:71]
	v_mfma_f32_16x16x32_bf16 v[64:67], v[178:181], v[210:213], v[64:67]
	s_barrier
	s_setprio 0
	s_mov_b32 m0, s87
	v_lshl_add_u64 v[138:139], v[138:139], 0, s[16:17]
	ds_read_b128 v[182:185], v146 offset:49152
	ds_read_b128 v[186:189], v146 offset:50176
	ds_read_b128 v[190:193], v146 offset:51200
	ds_read_b128 v[194:197], v146 offset:52224
	ds_read_b128 v[198:201], v146 offset:53248
	ds_read_b128 v[202:205], v146 offset:54272
	ds_read_b128 v[206:209], v146 offset:55296
	ds_read_b128 v[210:213], v146 offset:56320
	global_load_lds_dwordx4 v[138:139], off
	v_lshl_add_u64 v[138:139], v[214:215], 0, s[16:17]
	s_mov_b32 m0, s85
	s_nop 0
	global_load_lds_dwordx4 v[138:139], off
	v_lshl_add_u64 v[138:139], s[46:47], 0, v[130:131]
	s_mov_b32 m0, s86
	s_nop 0
	global_load_lds_dwordx4 v[138:139], off
	v_lshl_add_u64 v[138:139], s[46:47], 0, v[128:129]
	s_mov_b32 m0, s84
	s_nop 0
	global_load_lds_dwordx4 v[138:139], off
	v_lshl_add_u64 v[138:139], v[216:217], 0, s[16:17]
	s_mov_b32 m0, s70
	s_nop 0
	global_load_lds_dwordx4 v[138:139], off
	v_lshl_add_u64 v[138:139], v[218:219], 0, s[16:17]
	s_mov_b32 m0, s71
	s_nop 0
	global_load_lds_dwordx4 v[138:139], off
	s_waitcnt vmcnt(8)
	s_waitcnt lgkmcnt(0)
	s_setprio 1
	s_barrier
	v_mfma_f32_16x16x32_bf16 v[60:63], v[150:153], v[182:185], v[60:63]
	v_mfma_f32_16x16x32_bf16 v[56:59], v[158:161], v[182:185], v[56:59]
	v_mfma_f32_16x16x32_bf16 v[44:47], v[150:153], v[190:193], v[44:47]
	v_mfma_f32_16x16x32_bf16 v[40:43], v[158:161], v[190:193], v[40:43]
	v_mfma_f32_16x16x32_bf16 v[28:31], v[150:153], v[198:201], v[28:31]
	v_mfma_f32_16x16x32_bf16 v[24:27], v[158:161], v[198:201], v[24:27]
	v_mfma_f32_16x16x32_bf16 v[12:15], v[150:153], v[206:209], v[12:15]
	v_mfma_f32_16x16x32_bf16 v[8:11], v[158:161], v[206:209], v[8:11]
	v_mfma_f32_16x16x32_bf16 v[60:63], v[154:157], v[186:189], v[60:63]
	v_mfma_f32_16x16x32_bf16 v[56:59], v[162:165], v[186:189], v[56:59]
	v_mfma_f32_16x16x32_bf16 v[44:47], v[154:157], v[194:197], v[44:47]
	v_mfma_f32_16x16x32_bf16 v[40:43], v[162:165], v[194:197], v[40:43]
	v_mfma_f32_16x16x32_bf16 v[28:31], v[154:157], v[202:205], v[28:31]
	v_mfma_f32_16x16x32_bf16 v[24:27], v[162:165], v[202:205], v[24:27]
	v_mfma_f32_16x16x32_bf16 v[12:15], v[154:157], v[210:213], v[12:15]
	v_mfma_f32_16x16x32_bf16 v[8:11], v[162:165], v[210:213], v[8:11]
	v_mfma_f32_16x16x32_bf16 v[52:55], v[166:169], v[182:185], v[52:55]
	v_mfma_f32_16x16x32_bf16 v[48:51], v[174:177], v[182:185], v[48:51]
	v_mfma_f32_16x16x32_bf16 v[36:39], v[166:169], v[190:193], v[36:39]
	v_mfma_f32_16x16x32_bf16 v[32:35], v[174:177], v[190:193], v[32:35]
	v_mfma_f32_16x16x32_bf16 v[20:23], v[166:169], v[198:201], v[20:23]
	v_mfma_f32_16x16x32_bf16 v[16:19], v[174:177], v[198:201], v[16:19]
	v_mfma_f32_16x16x32_bf16 v[4:7], v[166:169], v[206:209], v[4:7]
	v_mfma_f32_16x16x32_bf16 v[0:3], v[174:177], v[206:209], v[0:3]
	v_mfma_f32_16x16x32_bf16 v[52:55], v[170:173], v[186:189], v[52:55]
	v_mfma_f32_16x16x32_bf16 v[48:51], v[178:181], v[186:189], v[48:51]
	v_mfma_f32_16x16x32_bf16 v[36:39], v[170:173], v[194:197], v[36:39]
	v_mfma_f32_16x16x32_bf16 v[32:35], v[178:181], v[194:197], v[32:35]
	v_mfma_f32_16x16x32_bf16 v[20:23], v[170:173], v[202:205], v[20:23]
	v_mfma_f32_16x16x32_bf16 v[16:19], v[178:181], v[202:205], v[16:19]
	v_mfma_f32_16x16x32_bf16 v[4:7], v[170:173], v[210:213], v[4:7]
	v_mfma_f32_16x16x32_bf16 v[0:3], v[178:181], v[210:213], v[0:3]
	s_barrier
	s_setprio 0
	s_andn2_b64 vcc, exec, s[44:45]
	s_mov_b64 s[46:47], -1
	s_mov_b64 s[44:45], 0
	s_mov_b64 s[48:49], 0x100
	s_cbranch_vccz .LBB0_744
